# mem-attention unit: the 8 q-fragment loads are issued between the key loads and the key LDS writes (one round trip fewer per unit)
# speedup vs baseline: 1.0058x; 1.0058x over previous
.LBB0_660:
	v_lshl_add_u64 v[54:55], v[10:11], 0, v[2:3]
	global_load_dwordx4 v[200:203], v[54:55], off
	v_lshl_add_u64 v[54:55], v[4:5], 0, v[2:3]
	global_load_dwordx4 v[204:207], v[54:55], off
	v_lshl_add_u64 v[54:55], v[8:9], 0, v[2:3]
	global_load_dwordx4 v[208:211], v[54:55], off
	v_lshl_add_u64 v[54:55], v[6:7], 0, v[2:3]
	global_load_dwordx4 v[212:215], v[54:55], off
	v_lshl_add_u64 v[10:11], v[10:11], 0, s[12:13]
	v_lshl_add_u64 v[4:5], v[4:5], 0, s[12:13]
	v_lshl_add_u64 v[8:9], v[8:9], 0, s[12:13]
	v_lshl_add_u64 v[6:7], v[6:7], 0, s[12:13]
	v_lshl_add_u64 v[54:55], v[10:11], 0, v[2:3]
	global_load_dwordx4 v[216:219], v[54:55], off
	v_lshl_add_u64 v[54:55], v[4:5], 0, v[2:3]
	global_load_dwordx4 v[220:223], v[54:55], off
	v_lshl_add_u64 v[54:55], v[8:9], 0, v[2:3]
	global_load_dwordx4 v[224:227], v[54:55], off
	v_lshl_add_u64 v[54:55], v[6:7], 0, v[2:3]
	global_load_dwordx4 v[228:231], v[54:55], off
	v_lshl_add_u64 v[10:11], v[10:11], 0, s[12:13]
	v_lshl_add_u64 v[4:5], v[4:5], 0, s[12:13]
	v_lshl_add_u64 v[8:9], v[8:9], 0, s[12:13]
	v_lshl_add_u64 v[6:7], v[6:7], 0, s[12:13]
	v_lshl_add_u64 v[54:55], v[10:11], 0, v[2:3]
	global_load_dwordx4 v[232:235], v[54:55], off
	v_lshl_add_u64 v[54:55], v[4:5], 0, v[2:3]
	global_load_dwordx4 v[236:239], v[54:55], off
	v_lshl_add_u64 v[54:55], v[8:9], 0, v[2:3]
	global_load_dwordx4 v[240:243], v[54:55], off
	v_lshl_add_u64 v[54:55], v[6:7], 0, v[2:3]
	global_load_dwordx4 v[244:247], v[54:55], off
	v_lshl_add_u64 v[10:11], v[10:11], 0, s[12:13]
	v_lshl_add_u64 v[4:5], v[4:5], 0, s[12:13]
	v_lshl_add_u64 v[8:9], v[8:9], 0, s[12:13]
	v_lshl_add_u64 v[6:7], v[6:7], 0, s[12:13]
	v_lshl_add_u64 v[54:55], v[10:11], 0, v[2:3]
	global_load_dwordx4 v[38:41], v[54:55], off
	v_lshl_add_u64 v[54:55], v[4:5], 0, v[2:3]
	global_load_dwordx4 v[42:45], v[54:55], off
	v_lshl_add_u64 v[54:55], v[8:9], 0, v[2:3]
	global_load_dwordx4 v[46:49], v[54:55], off
	v_lshl_add_u64 v[54:55], v[6:7], 0, v[2:3]
	global_load_dwordx4 v[50:53], v[54:55], off
	s_or_b64 exec, exec, s[20:21]
	s_lshl_b32 s20, s42, 7
	s_and_b32 s20, s20, 0xf80
	s_and_b32 s45, s23, 3
	s_add_i32 s44, s20, s28
	s_lshl_b32 s20, s22, 8
	s_lshl_b32 s43, s22, 12
	s_lshl_b32 s0, s0, 18
	s_ashr_i32 s21, s20, 31
	s_add_i32 s44, s44, s43
	s_lshl_b32 s46, s45, 9
	s_add_u32 s22, s29, s46
	s_addc_u32 s23, s30, 0
	v_or_b32_e32 v190, s44, v106
	v_mov_b64_e32 v[2:3], s[22:23]
	v_mad_i64_i32 v[2:3], s[22:23], v190, s39, v[2:3]
	v_mov_b32_e32 v103, v91
	v_lshl_add_u64 v[2:3], v[2:3], 0, v[102:103]
	global_load_dwordx4 v[58:61], v[2:3], off
	global_load_dwordx4 v[86:89], v[2:3], off offset:64
	global_load_dwordx4 v[82:85], v[2:3], off offset:128
	global_load_dwordx4 v[78:81], v[2:3], off offset:192
	global_load_dwordx4 v[74:77], v[2:3], off offset:256
	global_load_dwordx4 v[70:73], v[2:3], off offset:320
	global_load_dwordx4 v[62:65], v[2:3], off offset:384
	global_load_dwordx4 v[66:69], v[2:3], off offset:448
	v_add_u32_e32 v56, v15, v90
	s_waitcnt vmcnt(23)
	ds_write_b128 v56, v[200:203]
	v_add_u32_e32 v56, v16, v90
	s_waitcnt vmcnt(22)
	ds_write_b128 v56, v[204:207]
	v_add_u32_e32 v56, v14, v90
	s_waitcnt vmcnt(21)
	ds_write_b128 v56, v[208:211]
	v_add_u32_e32 v56, v13, v90
	s_waitcnt vmcnt(20)
	ds_write_b128 v56, v[212:215]
	v_add_u32_e32 v15, 0x8400, v15
	v_add_u32_e32 v16, 0x8400, v16
	v_add_u32_e32 v14, 0x8400, v14
	v_add_u32_e32 v13, 0x8400, v13
	v_add_u32_e32 v56, v15, v90
	s_waitcnt vmcnt(19)
	ds_write_b128 v56, v[216:219]
	v_add_u32_e32 v56, v16, v90
	s_waitcnt vmcnt(18)
	ds_write_b128 v56, v[220:223]
	v_add_u32_e32 v56, v14, v90
	s_waitcnt vmcnt(17)
	ds_write_b128 v56, v[224:227]
	v_add_u32_e32 v56, v13, v90
	s_waitcnt vmcnt(16)
	ds_write_b128 v56, v[228:231]
	v_add_u32_e32 v15, 0x8400, v15
	v_add_u32_e32 v16, 0x8400, v16
	v_add_u32_e32 v14, 0x8400, v14
	v_add_u32_e32 v13, 0x8400, v13
	v_add_u32_e32 v56, v15, v90
	s_waitcnt vmcnt(15)
	ds_write_b128 v56, v[232:235]
	v_add_u32_e32 v56, v16, v90
	s_waitcnt vmcnt(14)
	ds_write_b128 v56, v[236:239]
	v_add_u32_e32 v56, v14, v90
	s_waitcnt vmcnt(13)
	ds_write_b128 v56, v[240:243]
	v_add_u32_e32 v56, v13, v90
	s_waitcnt vmcnt(12)
	ds_write_b128 v56, v[244:247]
	v_add_u32_e32 v15, 0x8400, v15
	v_add_u32_e32 v16, 0x8400, v16
	v_add_u32_e32 v14, 0x8400, v14
	v_add_u32_e32 v13, 0x8400, v13
	v_add_u32_e32 v56, v15, v90
	s_waitcnt vmcnt(11)
	ds_write_b128 v56, v[38:41]
	v_add_u32_e32 v56, v16, v90
	s_waitcnt vmcnt(10)
	ds_write_b128 v56, v[42:45]
	v_add_u32_e32 v56, v14, v90
	s_waitcnt vmcnt(9)
	ds_write_b128 v56, v[46:49]
	v_add_u32_e32 v56, v13, v90
	s_waitcnt vmcnt(8)
	ds_write_b128 v56, v[50:53]
	s_waitcnt lgkmcnt(0)
	s_barrier
	ds_read_b128 v[2:5], v108
	ds_read_b128 v[6:9], v108 offset:64
	ds_read_b128 v[10:13], v108 offset:8448
	ds_read_b128 v[14:17], v108 offset:8512
	s_waitcnt vmcnt(7) lgkmcnt(3)
	v_mfma_f32_16x16x32_bf16 v[2:5], v[2:5], v[58:61], 0
	s_waitcnt lgkmcnt(1)
	v_mfma_f32_16x16x32_bf16 v[10:13], v[10:13], v[58:61], 0
	s_waitcnt vmcnt(6)
	v_mfma_f32_16x16x32_bf16 v[2:5], v[6:9], v[86:89], v[2:5]
	s_waitcnt lgkmcnt(0)
	v_mfma_f32_16x16x32_bf16 v[6:9], v[14:17], v[86:89], v[10:13]
	s_nop 3
	ds_read_b128 v[10:13], v108 offset:128
	ds_read_b128 v[14:17], v108 offset:192
	s_waitcnt vmcnt(5) lgkmcnt(1)
	v_mfma_f32_16x16x32_bf16 v[2:5], v[10:13], v[82:85], v[2:5]
	ds_read_b128 v[10:13], v108 offset:8576
	ds_read_b128 v[18:21], v108 offset:8640
	s_waitcnt lgkmcnt(1)
	v_mfma_f32_16x16x32_bf16 v[6:9], v[10:13], v[82:85], v[6:9]
	s_waitcnt vmcnt(4)
	v_mfma_f32_16x16x32_bf16 v[2:5], v[14:17], v[78:81], v[2:5]
	ds_read_b128 v[10:13], v108 offset:256
	ds_read_b128 v[14:17], v108 offset:320
	s_waitcnt lgkmcnt(2)
	v_mfma_f32_16x16x32_bf16 v[6:9], v[18:21], v[78:81], v[6:9]
	s_waitcnt vmcnt(3) lgkmcnt(1)
	v_mfma_f32_16x16x32_bf16 v[2:5], v[10:13], v[74:77], v[2:5]
	ds_read_b128 v[10:13], v108 offset:8704
	ds_read_b128 v[18:21], v108 offset:8768
	s_waitcnt lgkmcnt(1)
	v_mfma_f32_16x16x32_bf16 v[6:9], v[10:13], v[74:77], v[6:9]
	s_waitcnt vmcnt(2)
	v_mfma_f32_16x16x32_bf16 v[2:5], v[14:17], v[70:73], v[2:5]
	ds_read_b128 v[10:13], v108 offset:384
	ds_read_b128 v[14:17], v108 offset:448
	s_waitcnt lgkmcnt(2)
	v_mfma_f32_16x16x32_bf16 v[6:9], v[18:21], v[70:73], v[6:9]
	s_waitcnt vmcnt(1) lgkmcnt(1)
	v_mfma_f32_16x16x32_bf16 v[2:5], v[10:13], v[62:65], v[2:5]
	ds_read_b128 v[10:13], v108 offset:8832
	ds_read_b128 v[18:21], v108 offset:8896
	s_waitcnt lgkmcnt(1)
	v_mfma_f32_16x16x32_bf16 v[10:13], v[10:13], v[62:65], v[6:9]
	s_waitcnt vmcnt(0)
	v_mfma_f32_16x16x32_bf16 v[6:9], v[14:17], v[66:69], v[2:5]
	s_waitcnt lgkmcnt(0)
	v_mfma_f32_16x16x32_bf16 v[2:5], v[18:21], v[66:69], v[10:13]
	s_nop 3
	ds_read_b128 v[10:13], v108 offset:16896
	ds_read_b128 v[14:17], v108 offset:16960
	ds_read_b128 v[18:21], v108 offset:25344
	ds_read_b128 v[22:25], v108 offset:25408
	ds_read_b128 v[26:29], v108 offset:17024
	s_waitcnt lgkmcnt(4)
	v_mfma_f32_16x16x32_bf16 v[10:13], v[10:13], v[58:61], 0
	s_waitcnt lgkmcnt(3)
	v_mfma_f32_16x16x32_bf16 v[10:13], v[14:17], v[86:89], v[10:13]
	ds_read_b128 v[14:17], v108 offset:17088
	s_waitcnt lgkmcnt(1)
	v_mfma_f32_16x16x32_bf16 v[10:13], v[26:29], v[82:85], v[10:13]
	ds_read_b128 v[26:29], v108 offset:17152
	v_mfma_f32_16x16x32_bf16 v[18:21], v[18:21], v[58:61], 0
	s_waitcnt lgkmcnt(1)
	v_mfma_f32_16x16x32_bf16 v[10:13], v[14:17], v[78:81], v[10:13]
	ds_read_b128 v[14:17], v108 offset:17216
	s_waitcnt lgkmcnt(1)
	v_mfma_f32_16x16x32_bf16 v[10:13], v[26:29], v[74:77], v[10:13]
	ds_read_b128 v[26:29], v108 offset:17280
	s_waitcnt lgkmcnt(1)
	v_mfma_f32_16x16x32_bf16 v[10:13], v[14:17], v[70:73], v[10:13]
	ds_read_b128 v[14:17], v108 offset:17344
	s_waitcnt lgkmcnt(1)
	v_mfma_f32_16x16x32_bf16 v[10:13], v[26:29], v[62:65], v[10:13]
	s_waitcnt lgkmcnt(0)
	v_mfma_f32_16x16x32_bf16 v[10:13], v[14:17], v[66:69], v[10:13]
	ds_read_b128 v[14:17], v108 offset:25472
	v_mfma_f32_16x16x32_bf16 v[18:21], v[22:25], v[86:89], v[18:21]
	ds_read_b128 v[22:25], v108 offset:25536
	s_waitcnt lgkmcnt(1)
	v_mfma_f32_16x16x32_bf16 v[14:17], v[14:17], v[82:85], v[18:21]
	s_nop 4
	ds_read_b128 v[18:21], v108 offset:25600
	s_waitcnt lgkmcnt(1)
	v_mfma_f32_16x16x32_bf16 v[14:17], v[22:25], v[78:81], v[14:17]
	ds_read_b128 v[22:25], v108 offset:25664
	s_waitcnt lgkmcnt(1)
	v_mfma_f32_16x16x32_bf16 v[14:17], v[18:21], v[74:77], v[14:17]
	ds_read_b128 v[18:21], v108 offset:25728
	s_waitcnt lgkmcnt(1)
	v_mfma_f32_16x16x32_bf16 v[14:17], v[22:25], v[70:73], v[14:17]
	ds_read_b128 v[22:25], v108 offset:25792
	s_waitcnt lgkmcnt(1)
	v_mfma_f32_16x16x32_bf16 v[14:17], v[18:21], v[62:65], v[14:17]
	s_waitcnt lgkmcnt(0)
	v_mfma_f32_16x16x32_bf16 v[14:17], v[22:25], v[66:69], v[14:17]
	ds_read_b128 v[18:21], v108 offset:33792
	ds_read_b128 v[22:25], v108 offset:33856
	ds_read_b128 v[26:29], v108 offset:42240
	ds_read_b128 v[30:33], v108 offset:42304
	ds_read_b128 v[34:37], v108 offset:33920
	s_waitcnt lgkmcnt(4)
	v_mfma_f32_16x16x32_bf16 v[18:21], v[18:21], v[58:61], 0
	s_waitcnt lgkmcnt(3)
	v_mfma_f32_16x16x32_bf16 v[18:21], v[22:25], v[86:89], v[18:21]
	ds_read_b128 v[22:25], v108 offset:33984
	s_waitcnt lgkmcnt(1)
	v_mfma_f32_16x16x32_bf16 v[18:21], v[34:37], v[82:85], v[18:21]
	ds_read_b128 v[34:37], v108 offset:34048
	v_mfma_f32_16x16x32_bf16 v[26:29], v[26:29], v[58:61], 0
	s_waitcnt lgkmcnt(1)
	v_mfma_f32_16x16x32_bf16 v[18:21], v[22:25], v[78:81], v[18:21]
	ds_read_b128 v[22:25], v108 offset:34112
	s_waitcnt lgkmcnt(1)
	v_mfma_f32_16x16x32_bf16 v[18:21], v[34:37], v[74:77], v[18:21]
	ds_read_b128 v[34:37], v108 offset:34176
	s_waitcnt lgkmcnt(1)
	v_mfma_f32_16x16x32_bf16 v[18:21], v[22:25], v[70:73], v[18:21]
	ds_read_b128 v[22:25], v108 offset:34240
	s_waitcnt lgkmcnt(1)
	v_mfma_f32_16x16x32_bf16 v[18:21], v[34:37], v[62:65], v[18:21]
	s_waitcnt lgkmcnt(0)
	v_mfma_f32_16x16x32_bf16 v[18:21], v[22:25], v[66:69], v[18:21]
	ds_read_b128 v[22:25], v108 offset:42368
	v_mfma_f32_16x16x32_bf16 v[26:29], v[30:33], v[86:89], v[26:29]
	ds_read_b128 v[30:33], v108 offset:42432
	s_waitcnt lgkmcnt(1)
	v_mfma_f32_16x16x32_bf16 v[22:25], v[22:25], v[82:85], v[26:29]
	s_nop 4
	ds_read_b128 v[26:29], v108 offset:42496
	s_waitcnt lgkmcnt(1)
	v_mfma_f32_16x16x32_bf16 v[22:25], v[30:33], v[78:81], v[22:25]
	ds_read_b128 v[30:33], v108 offset:42560
	s_waitcnt lgkmcnt(1)
	v_mfma_f32_16x16x32_bf16 v[22:25], v[26:29], v[74:77], v[22:25]
	ds_read_b128 v[26:29], v108 offset:42624
	s_waitcnt lgkmcnt(1)
	v_mfma_f32_16x16x32_bf16 v[22:25], v[30:33], v[70:73], v[22:25]
	ds_read_b128 v[30:33], v108 offset:42688
	s_waitcnt lgkmcnt(1)
	v_mfma_f32_16x16x32_bf16 v[22:25], v[26:29], v[62:65], v[22:25]
	s_waitcnt lgkmcnt(0)
	v_mfma_f32_16x16x32_bf16 v[22:25], v[30:33], v[66:69], v[22:25]
	ds_read_b128 v[26:29], v108 offset:50688
	ds_read_b128 v[30:33], v108 offset:50752
	ds_read_b128 v[34:37], v108 offset:59136
	ds_read_b128 v[38:41], v108 offset:59200
	ds_read_b128 v[42:45], v108 offset:50816
	s_waitcnt lgkmcnt(4)
	v_mfma_f32_16x16x32_bf16 v[26:29], v[26:29], v[58:61], 0
	s_waitcnt lgkmcnt(3)
	v_mfma_f32_16x16x32_bf16 v[26:29], v[30:33], v[86:89], v[26:29]
	ds_read_b128 v[30:33], v108 offset:50880
	s_waitcnt lgkmcnt(1)
	v_mfma_f32_16x16x32_bf16 v[26:29], v[42:45], v[82:85], v[26:29]
	ds_read_b128 v[42:45], v108 offset:50944
	v_mfma_f32_16x16x32_bf16 v[34:37], v[34:37], v[58:61], 0
	s_waitcnt lgkmcnt(1)
	v_mfma_f32_16x16x32_bf16 v[26:29], v[30:33], v[78:81], v[26:29]
	ds_read_b128 v[30:33], v108 offset:51008
	s_waitcnt lgkmcnt(1)
	v_mfma_f32_16x16x32_bf16 v[26:29], v[42:45], v[74:77], v[26:29]
	ds_read_b128 v[42:45], v108 offset:51072
	s_waitcnt lgkmcnt(1)
	v_mfma_f32_16x16x32_bf16 v[26:29], v[30:33], v[70:73], v[26:29]
	ds_read_b128 v[30:33], v108 offset:51136
	s_waitcnt lgkmcnt(1)
	v_mfma_f32_16x16x32_bf16 v[26:29], v[42:45], v[62:65], v[26:29]
	s_waitcnt lgkmcnt(0)
	v_mfma_f32_16x16x32_bf16 v[26:29], v[30:33], v[66:69], v[26:29]
	ds_read_b128 v[30:33], v108 offset:59264
	v_mfma_f32_16x16x32_bf16 v[34:37], v[38:41], v[86:89], v[34:37]
	ds_read_b128 v[38:41], v108 offset:59328
	s_waitcnt lgkmcnt(1)
	v_mfma_f32_16x16x32_bf16 v[30:33], v[30:33], v[82:85], v[34:37]
	s_nop 4
	ds_read_b128 v[34:37], v108 offset:59392
	s_waitcnt lgkmcnt(1)
	v_mfma_f32_16x16x32_bf16 v[30:33], v[38:41], v[78:81], v[30:33]
	ds_read_b128 v[38:41], v108 offset:59456
	s_waitcnt lgkmcnt(1)
	v_mfma_f32_16x16x32_bf16 v[30:33], v[34:37], v[74:77], v[30:33]
	ds_read_b128 v[34:37], v108 offset:59520
	s_waitcnt lgkmcnt(1)
	v_mfma_f32_16x16x32_bf16 v[30:33], v[38:41], v[70:73], v[30:33]
	ds_read_b128 v[38:41], v108 offset:59584
	s_waitcnt lgkmcnt(1)
	v_mfma_f32_16x16x32_bf16 v[30:33], v[34:37], v[62:65], v[30:33]
	s_waitcnt lgkmcnt(0)
	v_mfma_f32_16x16x32_bf16 v[30:33], v[38:41], v[66:69], v[30:33]
	ds_read_b128 v[34:37], v109
	ds_read_b128 v[38:41], v110
	ds_read_b128 v[42:45], v117
	ds_read_b128 v[46:49], v118
	ds_read_b128 v[50:53], v111
	s_waitcnt lgkmcnt(4)
	v_mfma_f32_16x16x32_bf16 v[34:37], v[34:37], v[58:61], 0
	s_waitcnt lgkmcnt(3)
	v_mfma_f32_16x16x32_bf16 v[34:37], v[38:41], v[86:89], v[34:37]
	ds_read_b128 v[38:41], v112
	s_waitcnt lgkmcnt(1)
	v_mfma_f32_16x16x32_bf16 v[34:37], v[50:53], v[82:85], v[34:37]
	ds_read_b128 v[50:53], v113
	v_mfma_f32_16x16x32_bf16 v[42:45], v[42:45], v[58:61], 0
	s_waitcnt lgkmcnt(1)
	v_mfma_f32_16x16x32_bf16 v[34:37], v[38:41], v[78:81], v[34:37]
	ds_read_b128 v[38:41], v114
	s_waitcnt lgkmcnt(1)
	v_mfma_f32_16x16x32_bf16 v[34:37], v[50:53], v[74:77], v[34:37]
	ds_read_b128 v[50:53], v115
	s_waitcnt lgkmcnt(1)
	v_mfma_f32_16x16x32_bf16 v[34:37], v[38:41], v[70:73], v[34:37]
	ds_read_b128 v[38:41], v116
	s_waitcnt lgkmcnt(1)
	v_mfma_f32_16x16x32_bf16 v[34:37], v[50:53], v[62:65], v[34:37]
	s_waitcnt lgkmcnt(0)
	v_mfma_f32_16x16x32_bf16 v[34:37], v[38:41], v[66:69], v[34:37]
	ds_read_b128 v[38:41], v119
	v_mfma_f32_16x16x32_bf16 v[42:45], v[46:49], v[86:89], v[42:45]
	ds_read_b128 v[46:49], v120
	s_waitcnt lgkmcnt(1)
	v_mfma_f32_16x16x32_bf16 v[38:41], v[38:41], v[82:85], v[42:45]
	s_nop 4
	ds_read_b128 v[42:45], v121
	s_waitcnt lgkmcnt(1)
	v_mfma_f32_16x16x32_bf16 v[38:41], v[46:49], v[78:81], v[38:41]
	ds_read_b128 v[46:49], v122
	s_waitcnt lgkmcnt(1)
	v_mfma_f32_16x16x32_bf16 v[38:41], v[42:45], v[74:77], v[38:41]
	ds_read_b128 v[42:45], v123
	s_waitcnt lgkmcnt(1)
	v_mfma_f32_16x16x32_bf16 v[38:41], v[46:49], v[70:73], v[38:41]
	ds_read_b128 v[46:49], v124
	s_waitcnt lgkmcnt(1)
	v_mfma_f32_16x16x32_bf16 v[38:41], v[42:45], v[62:65], v[38:41]
	s_waitcnt lgkmcnt(0)
	v_mfma_f32_16x16x32_bf16 v[38:41], v[46:49], v[66:69], v[38:41]
	ds_read_b128 v[42:45], v125
	ds_read_b128 v[46:49], v126
	ds_read_b128 v[50:53], v133
	ds_read_b128 v[54:57], v134
	ds_read_b128 v[200:203], v127
	s_waitcnt lgkmcnt(4)
	v_mfma_f32_16x16x32_bf16 v[42:45], v[42:45], v[58:61], 0
	s_waitcnt lgkmcnt(3)
	v_mfma_f32_16x16x32_bf16 v[42:45], v[46:49], v[86:89], v[42:45]
	ds_read_b128 v[46:49], v128
	s_waitcnt lgkmcnt(1)
	v_mfma_f32_16x16x32_bf16 v[42:45], v[200:203], v[82:85], v[42:45]
	ds_read_b128 v[200:203], v129
	v_mfma_f32_16x16x32_bf16 v[50:53], v[50:53], v[58:61], 0
	s_waitcnt lgkmcnt(1)
	v_mfma_f32_16x16x32_bf16 v[42:45], v[46:49], v[78:81], v[42:45]
	ds_read_b128 v[46:49], v130
	s_waitcnt lgkmcnt(1)
	v_mfma_f32_16x16x32_bf16 v[42:45], v[200:203], v[74:77], v[42:45]
	ds_read_b128 v[200:203], v131
	s_waitcnt lgkmcnt(1)
	v_mfma_f32_16x16x32_bf16 v[42:45], v[46:49], v[70:73], v[42:45]
	ds_read_b128 v[46:49], v132
	s_waitcnt lgkmcnt(1)
	v_mfma_f32_16x16x32_bf16 v[42:45], v[200:203], v[62:65], v[42:45]
	s_waitcnt lgkmcnt(0)
	v_mfma_f32_16x16x32_bf16 v[42:45], v[46:49], v[66:69], v[42:45]
	ds_read_b128 v[46:49], v135
	v_mfma_f32_16x16x32_bf16 v[50:53], v[54:57], v[86:89], v[50:53]
	ds_read_b128 v[54:57], v136
	s_waitcnt lgkmcnt(1)
	v_mfma_f32_16x16x32_bf16 v[46:49], v[46:49], v[82:85], v[50:53]
	s_nop 4
	ds_read_b128 v[50:53], v137
	s_waitcnt lgkmcnt(1)
	v_mfma_f32_16x16x32_bf16 v[46:49], v[54:57], v[78:81], v[46:49]
	ds_read_b128 v[54:57], v138
	s_waitcnt lgkmcnt(1)
	v_mfma_f32_16x16x32_bf16 v[46:49], v[50:53], v[74:77], v[46:49]
	ds_read_b128 v[50:53], v139
	s_waitcnt lgkmcnt(1)
	v_mfma_f32_16x16x32_bf16 v[46:49], v[54:57], v[70:73], v[46:49]
	ds_read_b128 v[54:57], v140
	s_waitcnt lgkmcnt(1)
	v_mfma_f32_16x16x32_bf16 v[46:49], v[50:53], v[62:65], v[46:49]
	s_waitcnt lgkmcnt(0)
	v_mfma_f32_16x16x32_bf16 v[46:49], v[54:57], v[66:69], v[46:49]
	ds_read_b128 v[50:53], v141
	ds_read_b128 v[54:57], v142
	ds_read_b128 v[200:203], v149
	ds_read_b128 v[204:207], v150
	ds_read_b128 v[208:211], v143
	s_waitcnt lgkmcnt(4)
	v_mfma_f32_16x16x32_bf16 v[50:53], v[50:53], v[58:61], 0
	s_waitcnt lgkmcnt(3)
	v_mfma_f32_16x16x32_bf16 v[50:53], v[54:57], v[86:89], v[50:53]
	ds_read_b128 v[54:57], v144
	s_waitcnt lgkmcnt(1)
	v_mfma_f32_16x16x32_bf16 v[50:53], v[208:211], v[82:85], v[50:53]
	ds_read_b128 v[208:211], v145
	v_mfma_f32_16x16x32_bf16 v[200:203], v[200:203], v[58:61], 0
	s_waitcnt lgkmcnt(1)
	v_mfma_f32_16x16x32_bf16 v[50:53], v[54:57], v[78:81], v[50:53]
	ds_read_b128 v[54:57], v146
	s_waitcnt lgkmcnt(1)
	v_mfma_f32_16x16x32_bf16 v[50:53], v[208:211], v[74:77], v[50:53]
	ds_read_b128 v[208:211], v147
	s_waitcnt lgkmcnt(1)
	v_mfma_f32_16x16x32_bf16 v[50:53], v[54:57], v[70:73], v[50:53]
	ds_read_b128 v[54:57], v148
	s_waitcnt lgkmcnt(1)
	v_mfma_f32_16x16x32_bf16 v[50:53], v[208:211], v[62:65], v[50:53]
	s_waitcnt lgkmcnt(0)
	v_mfma_f32_16x16x32_bf16 v[50:53], v[54:57], v[66:69], v[50:53]
	ds_read_b128 v[54:57], v151
	v_mfma_f32_16x16x32_bf16 v[200:203], v[204:207], v[86:89], v[200:203]
	ds_read_b128 v[204:207], v152
	s_waitcnt lgkmcnt(1)
	v_mfma_f32_16x16x32_bf16 v[54:57], v[54:57], v[82:85], v[200:203]
	s_nop 4
	ds_read_b128 v[200:203], v153
	s_waitcnt lgkmcnt(1)
	v_mfma_f32_16x16x32_bf16 v[54:57], v[204:207], v[78:81], v[54:57]
	ds_read_b128 v[204:207], v154
	s_waitcnt lgkmcnt(1)
	v_mfma_f32_16x16x32_bf16 v[54:57], v[200:203], v[74:77], v[54:57]
	ds_read_b128 v[200:203], v155
	s_waitcnt lgkmcnt(1)
	v_mfma_f32_16x16x32_bf16 v[54:57], v[204:207], v[70:73], v[54:57]
	ds_read_b128 v[204:207], v156
	s_waitcnt lgkmcnt(1)
	v_mfma_f32_16x16x32_bf16 v[54:57], v[200:203], v[62:65], v[54:57]
	s_waitcnt lgkmcnt(0)
	v_mfma_f32_16x16x32_bf16 v[54:57], v[204:207], v[66:69], v[54:57]
	ds_read_b128 v[200:203], v157
	ds_read_b128 v[204:207], v158
	ds_read_b128 v[208:211], v165
	ds_read_b128 v[212:215], v166
	s_waitcnt lgkmcnt(3)
	v_mfma_f32_16x16x32_bf16 v[200:203], v[200:203], v[58:61], 0
	s_waitcnt lgkmcnt(1)
	v_mfma_f32_16x16x32_bf16 v[208:211], v[208:211], v[58:61], 0
	ds_read_b128 v[58:61], v159
	v_mfma_f32_16x16x32_bf16 v[200:203], v[204:207], v[86:89], v[200:203]
	ds_read_b128 v[204:207], v160
	s_waitcnt lgkmcnt(1)
	v_mfma_f32_16x16x32_bf16 v[58:61], v[58:61], v[82:85], v[200:203]
	s_nop 4
	ds_read_b128 v[200:203], v161
	s_waitcnt lgkmcnt(1)
	v_mfma_f32_16x16x32_bf16 v[58:61], v[204:207], v[78:81], v[58:61]
	ds_read_b128 v[204:207], v162
	s_waitcnt lgkmcnt(1)
	v_mfma_f32_16x16x32_bf16 v[58:61], v[200:203], v[74:77], v[58:61]
	ds_read_b128 v[200:203], v163
	s_waitcnt lgkmcnt(1)
	v_mfma_f32_16x16x32_bf16 v[58:61], v[204:207], v[70:73], v[58:61]
	ds_read_b128 v[204:207], v164
	s_waitcnt lgkmcnt(1)
	v_mfma_f32_16x16x32_bf16 v[58:61], v[200:203], v[62:65], v[58:61]
	ds_read_b128 v[200:203], v167
	s_waitcnt lgkmcnt(1)
	v_mfma_f32_16x16x32_bf16 v[58:61], v[204:207], v[66:69], v[58:61]
	ds_read_b128 v[204:207], v168
	v_mfma_f32_16x16x32_bf16 v[86:89], v[212:215], v[86:89], v[208:211]
	s_waitcnt lgkmcnt(1)
	v_mfma_f32_16x16x32_bf16 v[82:85], v[200:203], v[82:85], v[86:89]
	s_waitcnt lgkmcnt(0)
	v_mfma_f32_16x16x32_bf16 v[78:81], v[204:207], v[78:81], v[82:85]
	s_nop 3
	ds_read_b128 v[86:89], v169
	s_nop 0
	ds_read_b128 v[82:85], v170
	s_waitcnt lgkmcnt(1)
	v_mfma_f32_16x16x32_bf16 v[74:77], v[86:89], v[74:77], v[78:81]
	s_nop 2
	ds_read_b128 v[78:81], v171
	s_waitcnt lgkmcnt(1)
	v_mfma_f32_16x16x32_bf16 v[70:73], v[82:85], v[70:73], v[74:77]
	s_nop 2
	ds_read_b128 v[74:77], v172
	s_waitcnt lgkmcnt(1)
	v_mfma_f32_16x16x32_bf16 v[62:65], v[78:81], v[62:65], v[70:73]
	s_waitcnt lgkmcnt(0)
	v_mfma_f32_16x16x32_bf16 v[62:65], v[74:77], v[66:69], v[62:65]
	s_barrier
	s_and_saveexec_b64 s[22:23], s[4:5]
	s_xor_b64 s[22:23], exec, s[22:23]
	s_cbranch_execz .LBB0_665
	s_lshl_b64 s[24:25], s[20:21], 1
	s_add_u32 s26, s0, s24
	s_addc_u32 s27, 0, s25
	v_lshl_add_u64 v[66:67], v[100:101], 0, s[26:27]
	s_mov_b64 s[26:27], 0
	v_mov_b32_e32 v68, v91
	v_mov_b32_e32 v69, v176
	v_mov_b32_e32 v90, v0

.LBB0_1443:
	v_lshl_add_u64 v[54:55], v[10:11], 0, v[2:3]
	global_load_dwordx4 v[200:203], v[54:55], off
	v_lshl_add_u64 v[54:55], v[4:5], 0, v[2:3]
	global_load_dwordx4 v[204:207], v[54:55], off
	v_lshl_add_u64 v[54:55], v[8:9], 0, v[2:3]
	global_load_dwordx4 v[208:211], v[54:55], off
	v_lshl_add_u64 v[54:55], v[6:7], 0, v[2:3]
	global_load_dwordx4 v[212:215], v[54:55], off
	v_lshl_add_u64 v[10:11], v[10:11], 0, s[12:13]
	v_lshl_add_u64 v[4:5], v[4:5], 0, s[12:13]
	v_lshl_add_u64 v[8:9], v[8:9], 0, s[12:13]
	v_lshl_add_u64 v[6:7], v[6:7], 0, s[12:13]
	v_lshl_add_u64 v[54:55], v[10:11], 0, v[2:3]
	global_load_dwordx4 v[216:219], v[54:55], off
	v_lshl_add_u64 v[54:55], v[4:5], 0, v[2:3]
	global_load_dwordx4 v[220:223], v[54:55], off
	v_lshl_add_u64 v[54:55], v[8:9], 0, v[2:3]
	global_load_dwordx4 v[224:227], v[54:55], off
	v_lshl_add_u64 v[54:55], v[6:7], 0, v[2:3]
	global_load_dwordx4 v[228:231], v[54:55], off
	v_lshl_add_u64 v[10:11], v[10:11], 0, s[12:13]
	v_lshl_add_u64 v[4:5], v[4:5], 0, s[12:13]
	v_lshl_add_u64 v[8:9], v[8:9], 0, s[12:13]
	v_lshl_add_u64 v[6:7], v[6:7], 0, s[12:13]
	v_lshl_add_u64 v[54:55], v[10:11], 0, v[2:3]
	global_load_dwordx4 v[232:235], v[54:55], off
	v_lshl_add_u64 v[54:55], v[4:5], 0, v[2:3]
	global_load_dwordx4 v[236:239], v[54:55], off
	v_lshl_add_u64 v[54:55], v[8:9], 0, v[2:3]
	global_load_dwordx4 v[240:243], v[54:55], off
	v_lshl_add_u64 v[54:55], v[6:7], 0, v[2:3]
	global_load_dwordx4 v[244:247], v[54:55], off
	v_lshl_add_u64 v[10:11], v[10:11], 0, s[12:13]
	v_lshl_add_u64 v[4:5], v[4:5], 0, s[12:13]
	v_lshl_add_u64 v[8:9], v[8:9], 0, s[12:13]
	v_lshl_add_u64 v[6:7], v[6:7], 0, s[12:13]
	v_lshl_add_u64 v[54:55], v[10:11], 0, v[2:3]
	global_load_dwordx4 v[38:41], v[54:55], off
	v_lshl_add_u64 v[54:55], v[4:5], 0, v[2:3]
	global_load_dwordx4 v[42:45], v[54:55], off
	v_lshl_add_u64 v[54:55], v[8:9], 0, v[2:3]
	global_load_dwordx4 v[46:49], v[54:55], off
	v_lshl_add_u64 v[54:55], v[6:7], 0, v[2:3]
	global_load_dwordx4 v[50:53], v[54:55], off
	s_or_b64 exec, exec, s[20:21]
	s_lshl_b32 s20, s42, 7
	s_and_b32 s20, s20, 0xf80
	s_and_b32 s45, s23, 3
	s_add_i32 s44, s20, s28
	s_lshl_b32 s20, s22, 8
	s_lshl_b32 s43, s22, 12
	s_lshl_b32 s0, s0, 18
	s_ashr_i32 s21, s20, 31
	s_add_i32 s44, s44, s43
	s_lshl_b32 s46, s45, 9
	s_add_u32 s22, s29, s46
	s_addc_u32 s23, s30, 0
	v_or_b32_e32 v190, s44, v106
	v_mov_b64_e32 v[2:3], s[22:23]
	v_mad_i64_i32 v[2:3], s[22:23], v190, s39, v[2:3]
	v_mov_b32_e32 v103, v91
	v_lshl_add_u64 v[2:3], v[2:3], 0, v[102:103]
	global_load_dwordx4 v[58:61], v[2:3], off
	global_load_dwordx4 v[86:89], v[2:3], off offset:64
	global_load_dwordx4 v[82:85], v[2:3], off offset:128
	global_load_dwordx4 v[78:81], v[2:3], off offset:192
	global_load_dwordx4 v[74:77], v[2:3], off offset:256
	global_load_dwordx4 v[70:73], v[2:3], off offset:320
	global_load_dwordx4 v[62:65], v[2:3], off offset:384
	global_load_dwordx4 v[66:69], v[2:3], off offset:448
	v_add_u32_e32 v56, v15, v90
	s_waitcnt vmcnt(23)
	ds_write_b128 v56, v[200:203]
	v_add_u32_e32 v56, v16, v90
	s_waitcnt vmcnt(22)
	ds_write_b128 v56, v[204:207]
	v_add_u32_e32 v56, v14, v90
	s_waitcnt vmcnt(21)
	ds_write_b128 v56, v[208:211]
	v_add_u32_e32 v56, v13, v90
	s_waitcnt vmcnt(20)
	ds_write_b128 v56, v[212:215]
	v_add_u32_e32 v15, 0x8400, v15
	v_add_u32_e32 v16, 0x8400, v16
	v_add_u32_e32 v14, 0x8400, v14
	v_add_u32_e32 v13, 0x8400, v13
	v_add_u32_e32 v56, v15, v90
	s_waitcnt vmcnt(19)
	ds_write_b128 v56, v[216:219]
	v_add_u32_e32 v56, v16, v90
	s_waitcnt vmcnt(18)
	ds_write_b128 v56, v[220:223]
	v_add_u32_e32 v56, v14, v90
	s_waitcnt vmcnt(17)
	ds_write_b128 v56, v[224:227]
	v_add_u32_e32 v56, v13, v90
	s_waitcnt vmcnt(16)
	ds_write_b128 v56, v[228:231]
	v_add_u32_e32 v15, 0x8400, v15
	v_add_u32_e32 v16, 0x8400, v16
	v_add_u32_e32 v14, 0x8400, v14
	v_add_u32_e32 v13, 0x8400, v13
	v_add_u32_e32 v56, v15, v90
	s_waitcnt vmcnt(15)
	ds_write_b128 v56, v[232:235]
	v_add_u32_e32 v56, v16, v90
	s_waitcnt vmcnt(14)
	ds_write_b128 v56, v[236:239]
	v_add_u32_e32 v56, v14, v90
	s_waitcnt vmcnt(13)
	ds_write_b128 v56, v[240:243]
	v_add_u32_e32 v56, v13, v90
	s_waitcnt vmcnt(12)
	ds_write_b128 v56, v[244:247]
	v_add_u32_e32 v15, 0x8400, v15
	v_add_u32_e32 v16, 0x8400, v16
	v_add_u32_e32 v14, 0x8400, v14
	v_add_u32_e32 v13, 0x8400, v13
	v_add_u32_e32 v56, v15, v90
	s_waitcnt vmcnt(11)
	ds_write_b128 v56, v[38:41]
	v_add_u32_e32 v56, v16, v90
	s_waitcnt vmcnt(10)
	ds_write_b128 v56, v[42:45]
	v_add_u32_e32 v56, v14, v90
	s_waitcnt vmcnt(9)
	ds_write_b128 v56, v[46:49]
	v_add_u32_e32 v56, v13, v90
	s_waitcnt vmcnt(8)
	ds_write_b128 v56, v[50:53]
	s_waitcnt lgkmcnt(0)
	s_barrier
	ds_read_b128 v[2:5], v108
	ds_read_b128 v[6:9], v108 offset:64
	ds_read_b128 v[10:13], v108 offset:8448
	ds_read_b128 v[14:17], v108 offset:8512
	s_waitcnt vmcnt(7) lgkmcnt(3)
	v_mfma_f32_16x16x32_bf16 v[2:5], v[2:5], v[58:61], 0
	s_waitcnt lgkmcnt(1)
	v_mfma_f32_16x16x32_bf16 v[10:13], v[10:13], v[58:61], 0
	s_waitcnt vmcnt(6)
	v_mfma_f32_16x16x32_bf16 v[2:5], v[6:9], v[86:89], v[2:5]
	s_waitcnt lgkmcnt(0)
	v_mfma_f32_16x16x32_bf16 v[6:9], v[14:17], v[86:89], v[10:13]
	s_nop 3
	ds_read_b128 v[10:13], v108 offset:128
	ds_read_b128 v[14:17], v108 offset:192
	s_waitcnt vmcnt(5) lgkmcnt(1)
	v_mfma_f32_16x16x32_bf16 v[2:5], v[10:13], v[82:85], v[2:5]
	ds_read_b128 v[10:13], v108 offset:8576
	ds_read_b128 v[18:21], v108 offset:8640
	s_waitcnt lgkmcnt(1)
	v_mfma_f32_16x16x32_bf16 v[6:9], v[10:13], v[82:85], v[6:9]
	s_waitcnt vmcnt(4)
	v_mfma_f32_16x16x32_bf16 v[2:5], v[14:17], v[78:81], v[2:5]
	ds_read_b128 v[10:13], v108 offset:256
	ds_read_b128 v[14:17], v108 offset:320
	s_waitcnt lgkmcnt(2)
	v_mfma_f32_16x16x32_bf16 v[6:9], v[18:21], v[78:81], v[6:9]
	s_waitcnt vmcnt(3) lgkmcnt(1)
	v_mfma_f32_16x16x32_bf16 v[2:5], v[10:13], v[74:77], v[2:5]
	ds_read_b128 v[10:13], v108 offset:8704
	ds_read_b128 v[18:21], v108 offset:8768
	s_waitcnt lgkmcnt(1)
	v_mfma_f32_16x16x32_bf16 v[6:9], v[10:13], v[74:77], v[6:9]
	s_waitcnt vmcnt(2)
	v_mfma_f32_16x16x32_bf16 v[2:5], v[14:17], v[70:73], v[2:5]
	ds_read_b128 v[10:13], v108 offset:384
	ds_read_b128 v[14:17], v108 offset:448
	s_waitcnt lgkmcnt(2)
	v_mfma_f32_16x16x32_bf16 v[6:9], v[18:21], v[70:73], v[6:9]
	s_waitcnt vmcnt(1) lgkmcnt(1)
	v_mfma_f32_16x16x32_bf16 v[2:5], v[10:13], v[62:65], v[2:5]
	ds_read_b128 v[10:13], v108 offset:8832
	ds_read_b128 v[18:21], v108 offset:8896
	s_waitcnt lgkmcnt(1)
	v_mfma_f32_16x16x32_bf16 v[10:13], v[10:13], v[62:65], v[6:9]
	s_waitcnt vmcnt(0)
	v_mfma_f32_16x16x32_bf16 v[6:9], v[14:17], v[66:69], v[2:5]
	s_waitcnt lgkmcnt(0)
	v_mfma_f32_16x16x32_bf16 v[2:5], v[18:21], v[66:69], v[10:13]
	s_nop 3
	ds_read_b128 v[10:13], v108 offset:16896
	ds_read_b128 v[14:17], v108 offset:16960
	ds_read_b128 v[18:21], v108 offset:25344
	ds_read_b128 v[22:25], v108 offset:25408
	ds_read_b128 v[26:29], v108 offset:17024
	s_waitcnt lgkmcnt(4)
	v_mfma_f32_16x16x32_bf16 v[10:13], v[10:13], v[58:61], 0
	s_waitcnt lgkmcnt(3)
	v_mfma_f32_16x16x32_bf16 v[10:13], v[14:17], v[86:89], v[10:13]
	ds_read_b128 v[14:17], v108 offset:17088
	s_waitcnt lgkmcnt(1)
	v_mfma_f32_16x16x32_bf16 v[10:13], v[26:29], v[82:85], v[10:13]
	ds_read_b128 v[26:29], v108 offset:17152
	v_mfma_f32_16x16x32_bf16 v[18:21], v[18:21], v[58:61], 0
	s_waitcnt lgkmcnt(1)
	v_mfma_f32_16x16x32_bf16 v[10:13], v[14:17], v[78:81], v[10:13]
	ds_read_b128 v[14:17], v108 offset:17216
	s_waitcnt lgkmcnt(1)
	v_mfma_f32_16x16x32_bf16 v[10:13], v[26:29], v[74:77], v[10:13]
	ds_read_b128 v[26:29], v108 offset:17280
	s_waitcnt lgkmcnt(1)
	v_mfma_f32_16x16x32_bf16 v[10:13], v[14:17], v[70:73], v[10:13]
	ds_read_b128 v[14:17], v108 offset:17344
	s_waitcnt lgkmcnt(1)
	v_mfma_f32_16x16x32_bf16 v[10:13], v[26:29], v[62:65], v[10:13]
	s_waitcnt lgkmcnt(0)
	v_mfma_f32_16x16x32_bf16 v[10:13], v[14:17], v[66:69], v[10:13]
	ds_read_b128 v[14:17], v108 offset:25472
	v_mfma_f32_16x16x32_bf16 v[18:21], v[22:25], v[86:89], v[18:21]
	ds_read_b128 v[22:25], v108 offset:25536
	s_waitcnt lgkmcnt(1)
	v_mfma_f32_16x16x32_bf16 v[14:17], v[14:17], v[82:85], v[18:21]
	s_nop 4
	ds_read_b128 v[18:21], v108 offset:25600
	s_waitcnt lgkmcnt(1)
	v_mfma_f32_16x16x32_bf16 v[14:17], v[22:25], v[78:81], v[14:17]
	ds_read_b128 v[22:25], v108 offset:25664
	s_waitcnt lgkmcnt(1)
	v_mfma_f32_16x16x32_bf16 v[14:17], v[18:21], v[74:77], v[14:17]
	ds_read_b128 v[18:21], v108 offset:25728
	s_waitcnt lgkmcnt(1)
	v_mfma_f32_16x16x32_bf16 v[14:17], v[22:25], v[70:73], v[14:17]
	ds_read_b128 v[22:25], v108 offset:25792
	s_waitcnt lgkmcnt(1)
	v_mfma_f32_16x16x32_bf16 v[14:17], v[18:21], v[62:65], v[14:17]
	s_waitcnt lgkmcnt(0)
	v_mfma_f32_16x16x32_bf16 v[14:17], v[22:25], v[66:69], v[14:17]
	ds_read_b128 v[18:21], v108 offset:33792
	ds_read_b128 v[22:25], v108 offset:33856
	ds_read_b128 v[26:29], v108 offset:42240
	ds_read_b128 v[30:33], v108 offset:42304
	ds_read_b128 v[34:37], v108 offset:33920
	s_waitcnt lgkmcnt(4)
	v_mfma_f32_16x16x32_bf16 v[18:21], v[18:21], v[58:61], 0
	s_waitcnt lgkmcnt(3)
	v_mfma_f32_16x16x32_bf16 v[18:21], v[22:25], v[86:89], v[18:21]
	ds_read_b128 v[22:25], v108 offset:33984
	s_waitcnt lgkmcnt(1)
	v_mfma_f32_16x16x32_bf16 v[18:21], v[34:37], v[82:85], v[18:21]
	ds_read_b128 v[34:37], v108 offset:34048
	v_mfma_f32_16x16x32_bf16 v[26:29], v[26:29], v[58:61], 0
	s_waitcnt lgkmcnt(1)
	v_mfma_f32_16x16x32_bf16 v[18:21], v[22:25], v[78:81], v[18:21]
	ds_read_b128 v[22:25], v108 offset:34112
	s_waitcnt lgkmcnt(1)
	v_mfma_f32_16x16x32_bf16 v[18:21], v[34:37], v[74:77], v[18:21]
	ds_read_b128 v[34:37], v108 offset:34176
	s_waitcnt lgkmcnt(1)
	v_mfma_f32_16x16x32_bf16 v[18:21], v[22:25], v[70:73], v[18:21]
	ds_read_b128 v[22:25], v108 offset:34240
	s_waitcnt lgkmcnt(1)
	v_mfma_f32_16x16x32_bf16 v[18:21], v[34:37], v[62:65], v[18:21]
	s_waitcnt lgkmcnt(0)
	v_mfma_f32_16x16x32_bf16 v[18:21], v[22:25], v[66:69], v[18:21]
	ds_read_b128 v[22:25], v108 offset:42368
	v_mfma_f32_16x16x32_bf16 v[26:29], v[30:33], v[86:89], v[26:29]
	ds_read_b128 v[30:33], v108 offset:42432
	s_waitcnt lgkmcnt(1)
	v_mfma_f32_16x16x32_bf16 v[22:25], v[22:25], v[82:85], v[26:29]
	s_nop 4
	ds_read_b128 v[26:29], v108 offset:42496
	s_waitcnt lgkmcnt(1)
	v_mfma_f32_16x16x32_bf16 v[22:25], v[30:33], v[78:81], v[22:25]
	ds_read_b128 v[30:33], v108 offset:42560
	s_waitcnt lgkmcnt(1)
	v_mfma_f32_16x16x32_bf16 v[22:25], v[26:29], v[74:77], v[22:25]
	ds_read_b128 v[26:29], v108 offset:42624
	s_waitcnt lgkmcnt(1)
	v_mfma_f32_16x16x32_bf16 v[22:25], v[30:33], v[70:73], v[22:25]
	ds_read_b128 v[30:33], v108 offset:42688
	s_waitcnt lgkmcnt(1)
	v_mfma_f32_16x16x32_bf16 v[22:25], v[26:29], v[62:65], v[22:25]
	s_waitcnt lgkmcnt(0)
	v_mfma_f32_16x16x32_bf16 v[22:25], v[30:33], v[66:69], v[22:25]
	ds_read_b128 v[26:29], v108 offset:50688
	ds_read_b128 v[30:33], v108 offset:50752
	ds_read_b128 v[34:37], v108 offset:59136
	ds_read_b128 v[38:41], v108 offset:59200
	ds_read_b128 v[42:45], v108 offset:50816
	s_waitcnt lgkmcnt(4)
	v_mfma_f32_16x16x32_bf16 v[26:29], v[26:29], v[58:61], 0
	s_waitcnt lgkmcnt(3)
	v_mfma_f32_16x16x32_bf16 v[26:29], v[30:33], v[86:89], v[26:29]
	ds_read_b128 v[30:33], v108 offset:50880
	s_waitcnt lgkmcnt(1)
	v_mfma_f32_16x16x32_bf16 v[26:29], v[42:45], v[82:85], v[26:29]
	ds_read_b128 v[42:45], v108 offset:50944
	v_mfma_f32_16x16x32_bf16 v[34:37], v[34:37], v[58:61], 0
	s_waitcnt lgkmcnt(1)
	v_mfma_f32_16x16x32_bf16 v[26:29], v[30:33], v[78:81], v[26:29]
	ds_read_b128 v[30:33], v108 offset:51008
	s_waitcnt lgkmcnt(1)
	v_mfma_f32_16x16x32_bf16 v[26:29], v[42:45], v[74:77], v[26:29]
	ds_read_b128 v[42:45], v108 offset:51072
	s_waitcnt lgkmcnt(1)
	v_mfma_f32_16x16x32_bf16 v[26:29], v[30:33], v[70:73], v[26:29]
	ds_read_b128 v[30:33], v108 offset:51136
	s_waitcnt lgkmcnt(1)
	v_mfma_f32_16x16x32_bf16 v[26:29], v[42:45], v[62:65], v[26:29]
	s_waitcnt lgkmcnt(0)
	v_mfma_f32_16x16x32_bf16 v[26:29], v[30:33], v[66:69], v[26:29]
	ds_read_b128 v[30:33], v108 offset:59264
	v_mfma_f32_16x16x32_bf16 v[34:37], v[38:41], v[86:89], v[34:37]
	ds_read_b128 v[38:41], v108 offset:59328
	s_waitcnt lgkmcnt(1)
	v_mfma_f32_16x16x32_bf16 v[30:33], v[30:33], v[82:85], v[34:37]
	s_nop 4
	ds_read_b128 v[34:37], v108 offset:59392
	s_waitcnt lgkmcnt(1)
	v_mfma_f32_16x16x32_bf16 v[30:33], v[38:41], v[78:81], v[30:33]
	ds_read_b128 v[38:41], v108 offset:59456
	s_waitcnt lgkmcnt(1)
	v_mfma_f32_16x16x32_bf16 v[30:33], v[34:37], v[74:77], v[30:33]
	ds_read_b128 v[34:37], v108 offset:59520
	s_waitcnt lgkmcnt(1)
	v_mfma_f32_16x16x32_bf16 v[30:33], v[38:41], v[70:73], v[30:33]
	ds_read_b128 v[38:41], v108 offset:59584
	s_waitcnt lgkmcnt(1)
	v_mfma_f32_16x16x32_bf16 v[30:33], v[34:37], v[62:65], v[30:33]
	s_waitcnt lgkmcnt(0)
	v_mfma_f32_16x16x32_bf16 v[30:33], v[38:41], v[66:69], v[30:33]
	ds_read_b128 v[34:37], v109
	ds_read_b128 v[38:41], v110
	ds_read_b128 v[42:45], v117
	ds_read_b128 v[46:49], v118
	ds_read_b128 v[50:53], v111
	s_waitcnt lgkmcnt(4)
	v_mfma_f32_16x16x32_bf16 v[34:37], v[34:37], v[58:61], 0
	s_waitcnt lgkmcnt(3)
	v_mfma_f32_16x16x32_bf16 v[34:37], v[38:41], v[86:89], v[34:37]
	ds_read_b128 v[38:41], v112
	s_waitcnt lgkmcnt(1)
	v_mfma_f32_16x16x32_bf16 v[34:37], v[50:53], v[82:85], v[34:37]
	ds_read_b128 v[50:53], v113
	v_mfma_f32_16x16x32_bf16 v[42:45], v[42:45], v[58:61], 0
	s_waitcnt lgkmcnt(1)
	v_mfma_f32_16x16x32_bf16 v[34:37], v[38:41], v[78:81], v[34:37]
	ds_read_b128 v[38:41], v114
	s_waitcnt lgkmcnt(1)
	v_mfma_f32_16x16x32_bf16 v[34:37], v[50:53], v[74:77], v[34:37]
	ds_read_b128 v[50:53], v115
	s_waitcnt lgkmcnt(1)
	v_mfma_f32_16x16x32_bf16 v[34:37], v[38:41], v[70:73], v[34:37]
	ds_read_b128 v[38:41], v116
	s_waitcnt lgkmcnt(1)
	v_mfma_f32_16x16x32_bf16 v[34:37], v[50:53], v[62:65], v[34:37]
	s_waitcnt lgkmcnt(0)
	v_mfma_f32_16x16x32_bf16 v[34:37], v[38:41], v[66:69], v[34:37]
	ds_read_b128 v[38:41], v119
	v_mfma_f32_16x16x32_bf16 v[42:45], v[46:49], v[86:89], v[42:45]
	ds_read_b128 v[46:49], v120
	s_waitcnt lgkmcnt(1)
	v_mfma_f32_16x16x32_bf16 v[38:41], v[38:41], v[82:85], v[42:45]
	s_nop 4
	ds_read_b128 v[42:45], v121
	s_waitcnt lgkmcnt(1)
	v_mfma_f32_16x16x32_bf16 v[38:41], v[46:49], v[78:81], v[38:41]
	ds_read_b128 v[46:49], v122
	s_waitcnt lgkmcnt(1)
	v_mfma_f32_16x16x32_bf16 v[38:41], v[42:45], v[74:77], v[38:41]
	ds_read_b128 v[42:45], v123
	s_waitcnt lgkmcnt(1)
	v_mfma_f32_16x16x32_bf16 v[38:41], v[46:49], v[70:73], v[38:41]
	ds_read_b128 v[46:49], v124
	s_waitcnt lgkmcnt(1)
	v_mfma_f32_16x16x32_bf16 v[38:41], v[42:45], v[62:65], v[38:41]
	s_waitcnt lgkmcnt(0)
	v_mfma_f32_16x16x32_bf16 v[38:41], v[46:49], v[66:69], v[38:41]
	ds_read_b128 v[42:45], v125
	ds_read_b128 v[46:49], v126
	ds_read_b128 v[50:53], v133
	ds_read_b128 v[54:57], v134
	ds_read_b128 v[192:195], v127
	s_waitcnt lgkmcnt(4)
	v_mfma_f32_16x16x32_bf16 v[42:45], v[42:45], v[58:61], 0
	s_waitcnt lgkmcnt(3)
	v_mfma_f32_16x16x32_bf16 v[42:45], v[46:49], v[86:89], v[42:45]
	ds_read_b128 v[46:49], v128
	s_waitcnt lgkmcnt(1)
	v_mfma_f32_16x16x32_bf16 v[42:45], v[192:195], v[82:85], v[42:45]
	ds_read_b128 v[192:195], v129
	v_mfma_f32_16x16x32_bf16 v[50:53], v[50:53], v[58:61], 0
	s_waitcnt lgkmcnt(1)
	v_mfma_f32_16x16x32_bf16 v[42:45], v[46:49], v[78:81], v[42:45]
	ds_read_b128 v[46:49], v130
	s_waitcnt lgkmcnt(1)
	v_mfma_f32_16x16x32_bf16 v[42:45], v[192:195], v[74:77], v[42:45]
	ds_read_b128 v[192:195], v131
	s_waitcnt lgkmcnt(1)
	v_mfma_f32_16x16x32_bf16 v[42:45], v[46:49], v[70:73], v[42:45]
	ds_read_b128 v[46:49], v132
	s_waitcnt lgkmcnt(1)
	v_mfma_f32_16x16x32_bf16 v[42:45], v[192:195], v[62:65], v[42:45]
	s_waitcnt lgkmcnt(0)
	v_mfma_f32_16x16x32_bf16 v[42:45], v[46:49], v[66:69], v[42:45]
	ds_read_b128 v[46:49], v135
	v_mfma_f32_16x16x32_bf16 v[50:53], v[54:57], v[86:89], v[50:53]
	ds_read_b128 v[54:57], v136
	s_waitcnt lgkmcnt(1)
	v_mfma_f32_16x16x32_bf16 v[46:49], v[46:49], v[82:85], v[50:53]
	s_nop 4
	ds_read_b128 v[50:53], v137
	s_waitcnt lgkmcnt(1)
	v_mfma_f32_16x16x32_bf16 v[46:49], v[54:57], v[78:81], v[46:49]
	ds_read_b128 v[54:57], v138
	s_waitcnt lgkmcnt(1)
	v_mfma_f32_16x16x32_bf16 v[46:49], v[50:53], v[74:77], v[46:49]
	ds_read_b128 v[50:53], v139
	s_waitcnt lgkmcnt(1)
	v_mfma_f32_16x16x32_bf16 v[46:49], v[54:57], v[70:73], v[46:49]
	ds_read_b128 v[54:57], v140
	s_waitcnt lgkmcnt(1)
	v_mfma_f32_16x16x32_bf16 v[46:49], v[50:53], v[62:65], v[46:49]
	s_waitcnt lgkmcnt(0)
	v_mfma_f32_16x16x32_bf16 v[46:49], v[54:57], v[66:69], v[46:49]
	ds_read_b128 v[50:53], v141
	ds_read_b128 v[54:57], v142
	ds_read_b128 v[192:195], v149
	ds_read_b128 v[196:199], v150
	ds_read_b128 v[200:203], v143
	s_waitcnt lgkmcnt(4)
	v_mfma_f32_16x16x32_bf16 v[50:53], v[50:53], v[58:61], 0
	s_waitcnt lgkmcnt(3)
	v_mfma_f32_16x16x32_bf16 v[50:53], v[54:57], v[86:89], v[50:53]
	ds_read_b128 v[54:57], v144
	s_waitcnt lgkmcnt(1)
	v_mfma_f32_16x16x32_bf16 v[50:53], v[200:203], v[82:85], v[50:53]
	ds_read_b128 v[200:203], v145
	v_mfma_f32_16x16x32_bf16 v[192:195], v[192:195], v[58:61], 0
	s_waitcnt lgkmcnt(1)
	v_mfma_f32_16x16x32_bf16 v[50:53], v[54:57], v[78:81], v[50:53]
	ds_read_b128 v[54:57], v146
	s_waitcnt lgkmcnt(1)
	v_mfma_f32_16x16x32_bf16 v[50:53], v[200:203], v[74:77], v[50:53]
	ds_read_b128 v[200:203], v147
	s_waitcnt lgkmcnt(1)
	v_mfma_f32_16x16x32_bf16 v[50:53], v[54:57], v[70:73], v[50:53]
	ds_read_b128 v[54:57], v148
	s_waitcnt lgkmcnt(1)
	v_mfma_f32_16x16x32_bf16 v[50:53], v[200:203], v[62:65], v[50:53]
	s_waitcnt lgkmcnt(0)
	v_mfma_f32_16x16x32_bf16 v[50:53], v[54:57], v[66:69], v[50:53]
	ds_read_b128 v[54:57], v151
	v_mfma_f32_16x16x32_bf16 v[192:195], v[196:199], v[86:89], v[192:195]
	ds_read_b128 v[196:199], v152
	s_waitcnt lgkmcnt(1)
	v_mfma_f32_16x16x32_bf16 v[54:57], v[54:57], v[82:85], v[192:195]
	s_nop 4
	ds_read_b128 v[192:195], v153
	s_waitcnt lgkmcnt(1)
	v_mfma_f32_16x16x32_bf16 v[54:57], v[196:199], v[78:81], v[54:57]
	ds_read_b128 v[196:199], v154
	s_waitcnt lgkmcnt(1)
	v_mfma_f32_16x16x32_bf16 v[54:57], v[192:195], v[74:77], v[54:57]
	ds_read_b128 v[192:195], v155
	s_waitcnt lgkmcnt(1)
	v_mfma_f32_16x16x32_bf16 v[54:57], v[196:199], v[70:73], v[54:57]
	ds_read_b128 v[196:199], v156
	s_waitcnt lgkmcnt(1)
	v_mfma_f32_16x16x32_bf16 v[54:57], v[192:195], v[62:65], v[54:57]
	s_waitcnt lgkmcnt(0)
	v_mfma_f32_16x16x32_bf16 v[54:57], v[196:199], v[66:69], v[54:57]
	ds_read_b128 v[192:195], v157
	ds_read_b128 v[196:199], v158
	ds_read_b128 v[200:203], v165
	ds_read_b128 v[204:207], v166
	s_waitcnt lgkmcnt(3)
	v_mfma_f32_16x16x32_bf16 v[192:195], v[192:195], v[58:61], 0
	s_waitcnt lgkmcnt(1)
	v_mfma_f32_16x16x32_bf16 v[200:203], v[200:203], v[58:61], 0
	ds_read_b128 v[58:61], v159
	v_mfma_f32_16x16x32_bf16 v[192:195], v[196:199], v[86:89], v[192:195]
	ds_read_b128 v[196:199], v160
	s_waitcnt lgkmcnt(1)
	v_mfma_f32_16x16x32_bf16 v[58:61], v[58:61], v[82:85], v[192:195]
	s_nop 4
	ds_read_b128 v[192:195], v161
	s_waitcnt lgkmcnt(1)
	v_mfma_f32_16x16x32_bf16 v[58:61], v[196:199], v[78:81], v[58:61]
	ds_read_b128 v[196:199], v162
	s_waitcnt lgkmcnt(1)
	v_mfma_f32_16x16x32_bf16 v[58:61], v[192:195], v[74:77], v[58:61]
	ds_read_b128 v[192:195], v163
	s_waitcnt lgkmcnt(1)
	v_mfma_f32_16x16x32_bf16 v[58:61], v[196:199], v[70:73], v[58:61]
	ds_read_b128 v[196:199], v164
	s_waitcnt lgkmcnt(1)
	v_mfma_f32_16x16x32_bf16 v[58:61], v[192:195], v[62:65], v[58:61]
	ds_read_b128 v[192:195], v167
	s_waitcnt lgkmcnt(1)
	v_mfma_f32_16x16x32_bf16 v[58:61], v[196:199], v[66:69], v[58:61]
	ds_read_b128 v[196:199], v168
	v_mfma_f32_16x16x32_bf16 v[86:89], v[204:207], v[86:89], v[200:203]
	s_waitcnt lgkmcnt(1)
	v_mfma_f32_16x16x32_bf16 v[82:85], v[192:195], v[82:85], v[86:89]
	s_waitcnt lgkmcnt(0)
	v_mfma_f32_16x16x32_bf16 v[78:81], v[196:199], v[78:81], v[82:85]
	s_nop 3
	ds_read_b128 v[86:89], v169
	s_nop 0
	ds_read_b128 v[82:85], v170
	s_waitcnt lgkmcnt(1)
	v_mfma_f32_16x16x32_bf16 v[74:77], v[86:89], v[74:77], v[78:81]
	s_nop 2
	ds_read_b128 v[78:81], v171
	s_waitcnt lgkmcnt(1)
	v_mfma_f32_16x16x32_bf16 v[70:73], v[82:85], v[70:73], v[74:77]
	s_nop 2
	ds_read_b128 v[74:77], v172
	s_waitcnt lgkmcnt(1)
	v_mfma_f32_16x16x32_bf16 v[62:65], v[78:81], v[62:65], v[70:73]
	s_waitcnt lgkmcnt(0)
	v_mfma_f32_16x16x32_bf16 v[62:65], v[74:77], v[66:69], v[62:65]
	s_barrier
	s_and_saveexec_b64 s[24:25], s[4:5]
	s_xor_b64 s[24:25], exec, s[24:25]
	s_cbranch_execz .LBB0_1448
	s_lshl_b64 s[22:23], s[20:21], 1
	s_add_u32 s26, s0, s22
	s_addc_u32 s27, 0, s23
	v_lshl_add_u64 v[66:67], v[100:101], 0, s[26:27]
	s_mov_b64 s[26:27], 0
	v_mov_b32_e32 v68, v91
	v_mov_b32_e32 v69, v176
	v_mov_b32_e32 v90, v0
